# X + attention tile B: running row-sum pk_add chain moved behind the eight stage-1 S MFMAs (no longer in front of them)
# baseline (speedup 1.0000x reference)
;     ...
;     auto compute = [&](int buf, int t) {
;         const LAS bf16* Ks = (const LAS bf16*)(lds + koff(buf)); const LAS bf16* VT = (const LAS bf16*)(lds + voff(buf));
;         bf16x8 kf[2][4]; float bias[2][2][4];
; #pragma unroll
;         for (int kb = 0; kb < 2; ++kb)
; #pragma unroll
;             for (int ks = 0; ks < 4; ++ks) kf[kb][ks] = *(const LAS bf16x8*)(Ks + (32 * kh + 16 * kb + fr) * QP + 32 * ks + 8 * fq);
;         if (MODE == 0) { const LAS float* bp = BT + (2047 - 16 - (q0 + 32 * rp + fr - t * 64 - 32 * kh - 4 * fq));
; #pragma unroll
;                 for (int kb = 0; kb < 2; ++kb)
; #pragma unroll
;                     for (int i = 0; i < 4; ++i) bias[0][kb][i] = bp[16 * (kb + 1) + i]; }
;         __builtin_amdgcn_sched_barrier(0);
;         f32x4 s[2][2];
; #pragma unroll
;         for (int rb = 0; rb < 2; ++rb)
; #pragma unroll
;             for (int kb = 0; kb < 2; ++kb) s[rb][kb] = (f32x4){0.f, 0.f, 0.f, 0.f};
;         bf16x8 pf[2];
;         auto smax = [&](int rb) {
;             if (MODE == 0) { s[rb][0] = s[rb][0] + (f32x4){bias[rb][0][0], bias[rb][0][1], bias[rb][0][2], bias[rb][0][3]}; s[rb][1] = s[rb][1] + (f32x4){bias[rb][1][0], bias[rb][1][1], bias[rb][1][2], bias[rb][1][3]}; }
;             else { s[rb][0] = s[rb][0] - bref; s[rb][1] = s[rb][1] - bref; }
;             float ps = 0.f;
; #pragma unroll
;             for (int kb = 0; kb < 2; ++kb)
; #pragma unroll
;                 for (int i = 0; i < 4; ++i) { s[rb][kb][i] = __builtin_amdgcn_exp2f(s[rb][kb][i]); ps += s[rb][kb][i]; }
;             lrun[rb] += ps;
;             u32x4 pw; pw.x = pk2(s[rb][0][0], s[rb][0][1]); pw.y = pk2(s[rb][0][2], s[rb][0][3]); pw.z = pk2(s[rb][1][0], s[rb][1][1]); pw.w = pk2(s[rb][1][2], s[rb][1][3]);
;             pf[rb] = __builtin_bit_cast(bf16x8, pw); };
; #pragma unroll
;         for (int ks = 0; ks < 4; ++ks)
; #pragma unroll
;             for (int kb = 0; kb < 2; ++kb) MMA16(kf[kb][ks], qf[0][ks], s[0][kb]);
;         __builtin_amdgcn_sched_barrier(0);
;         bf16x8 vf[8];
; #pragma unroll
;         for (int db = 0; db < 8; ++db) vf[db] = *(const LAS bf16x8*)(VT + (16 * db + fr) * VPA + 32 * kh + 8 * fq);
;         if (MODE == 0) { const LAS float* bp = BT + (2047 - 16 - (q0 + 32 * rp + fr - t * 64 - 32 * kh - 4 * fq));
; #pragma unroll
;             for (int kb = 0; kb < 2; ++kb)
; #pragma unroll
.LBB0_121:
	s_add_i32 s78, s78, 0x9800
	s_cmp_lt_i32 s63, 2
	s_cselect_b32 s63, s78, 0
	s_add_i32 s63, s63, 0
	v_add_u32_e32 v171, s63, v165
	v_add_u32_e32 v182, v171, v167
	ds_read_b128 v[172:175], v182 offset:192
	ds_read_b128 v[192:195], v182 offset:4736
	ds_read_b128 v[196:199], v182 offset:4800
	ds_read2_b32 v[182:183], v170 offset0:80 offset1:81
	ds_read2_b32 v[184:185], v170 offset0:82 offset1:83
	ds_read2_b32 v[188:189], v170 offset0:96 offset1:97
	ds_read2_b32 v[190:191], v170 offset0:98 offset1:99
	s_waitcnt lgkmcnt(7)
	v_mfma_f32_16x16x32_bf16 v[200:203], v[228:231], v[76:79], 0
	v_mfma_f32_16x16x32_bf16 v[204:207], v[232:235], v[76:79], 0
	v_mfma_f32_16x16x32_bf16 v[200:203], v[240:243], v[80:83], v[200:203]
	v_mfma_f32_16x16x32_bf16 v[204:207], v[244:247], v[80:83], v[204:207]
	v_mfma_f32_16x16x32_bf16 v[200:203], v[248:251], v[84:87], v[200:203]
	s_waitcnt lgkmcnt(5)
	v_mfma_f32_16x16x32_bf16 v[204:207], v[192:195], v[84:87], v[204:207]
	v_mfma_f32_16x16x32_bf16 v[200:203], v[172:175], v[88:91], v[200:203]
	s_waitcnt lgkmcnt(4)
	v_mfma_f32_16x16x32_bf16 v[204:207], v[196:199], v[88:91], v[204:207]
	v_pk_add_f32 v[142:143], v[142:143], 0 op_sel_hi:[1,0]
	v_pk_add_f32 v[140:141], v[140:141], v[142:143]
	v_pk_add_f32 v[138:139], v[138:139], v[140:141]
	v_pk_add_f32 v[136:137], v[136:137], v[138:139]
	v_pk_add_f32 v[134:135], v[134:135], v[136:137]
	v_pk_add_f32 v[132:133], v[132:133], v[134:135]
	v_pk_add_f32 v[130:131], v[130:131], v[132:133]
	v_pk_add_f32 v[128:129], v[128:129], v[130:131]
	v_pk_add_f32 v[150:151], v[150:151], v[128:129]
	v_mfma_f32_16x16x32_bf16 v[208:211], v[228:231], v[92:95], 0
	ds_read2_b32 v[212:213], v170 offset0:64 offset1:65
	v_add3_u32 v171, v171, v168, v169
	s_waitcnt lgkmcnt(3)
	s_nop 1
	v_pk_add_f32 v[184:185], v[184:185], v[202:203]
	v_pk_add_f32 v[182:183], v[182:183], v[200:201]
	s_waitcnt lgkmcnt(1)
	v_pk_add_f32 v[190:191], v[190:191], v[206:207]
	v_mfma_f32_16x16x32_bf16 v[136:139], v[232:235], v[92:95], 0
	ds_read_b128 v[128:131], v171 offset:36352
	v_pk_add_f32 v[188:189], v[188:189], v[204:205]
	v_exp_f32_e32 v207, v182
	v_mfma_f32_16x16x32_bf16 v[200:203], v[240:243], v[96:99], v[208:211]
	ds_read_b128 v[132:135], v171 offset:18432
	v_exp_f32_e32 v183, v183
	v_exp_f32_e32 v185, v185
	v_mfma_f32_16x16x32_bf16 v[144:147], v[244:247], v[96:99], v[136:139]
	v_exp_f32_e32 v209, v184
	v_exp_f32_e32 v211, v188
	v_exp_f32_e32 v189, v189
	ds_read_b128 v[136:139], v171 offset:20992
	v_mfma_f32_16x16x32_bf16 v[200:203], v[248:251], v[100:103], v[200:203]
	ds_read_b128 v[140:143], v171 offset:23552
	v_exp_f32_e32 v191, v191
	v_mfma_f32_16x16x32_bf16 v[192:195], v[192:195], v[100:103], v[144:147]
	s_nop 2
	ds_read_b128 v[144:147], v171 offset:26112
	v_mfma_f32_16x16x32_bf16 v[192:195], v[196:199], v[104:107], v[192:195]
	v_mfma_f32_16x16x32_bf16 v[172:175], v[172:175], v[104:107], v[200:203]
	ds_read2_b32 v[196:197], v170 offset0:66 offset1:67
	s_waitcnt lgkmcnt(0)
	s_nop 5
	v_pk_add_f32 v[174:175], v[196:197], v[174:175]
	ds_read_b128 v[196:199], v171 offset:33792
	v_exp_f32_e32 v208, v174
	v_exp_f32_e32 v184, v175
	ds_read2_b32 v[174:175], v170 offset0:82 offset1:83
	s_waitcnt lgkmcnt(0)
	v_pk_add_f32 v[174:175], v[174:175], v[194:195]
	ds_read2_b32 v[204:205], v170 offset0:80 offset1:81
	s_waitcnt lgkmcnt(0)
	v_pk_add_f32 v[192:193], v[204:205], v[192:193]
	v_pk_add_f32 v[172:173], v[212:213], v[172:173]
	v_exp_f32_e32 v210, v192
	v_exp_f32_e32 v206, v172
	v_exp_f32_e32 v182, v173
	v_exp_f32_e32 v188, v193
	v_exp_f32_e32 v213, v190
	v_pk_add_f32 v[172:173], v[206:207], 0 op_sel_hi:[1,0]
	v_exp_f32_e32 v212, v174
	v_pk_add_f32 v[172:173], v[182:183], v[172:173]
	v_exp_f32_e32 v190, v175
	v_pk_add_f32 v[172:173], v[208:209], v[172:173]
	ds_read_b128 v[192:195], v171 offset:31232
	v_pk_add_f32 v[172:173], v[184:185], v[172:173]
	s_nop 0
	v_pk_add_f32 v[172:173], v[210:211], v[172:173]
	s_nop 0
	v_pk_add_f32 v[172:173], v[188:189], v[172:173]
	s_nop 0
	v_pk_add_f32 v[172:173], v[212:213], v[172:173]
	s_nop 0
	v_pk_add_f32 v[204:205], v[190:191], v[172:173]
	ds_read_b128 v[172:175], v171 offset:28672
	v_cvt_pk_bf16_f32 v200, v207, v183
	v_cvt_pk_bf16_f32 v201, v209, v185
	v_cvt_pk_bf16_f32 v202, v211, v189
	v_cvt_pk_bf16_f32 v203, v213, v191
	s_nop 0
	v_mfma_f32_16x16x32_bf16 v[124:127], v[132:135], v[200:203], v[124:127]
	v_add_f32_e64 v150, v150, v204
	v_add_f32_e64 v151, v151, v205
	v_cvt_pk_bf16_f32 v204, v206, v182
	v_cvt_pk_bf16_f32 v205, v208, v184
	v_mfma_f32_16x16x32_bf16 v[120:123], v[136:139], v[200:203], v[120:123]
	v_cvt_pk_bf16_f32 v206, v210, v188
	v_cvt_pk_bf16_f32 v207, v212, v190
	v_mfma_f32_16x16x32_bf16 v[116:119], v[140:143], v[200:203], v[116:119]
	v_mfma_f32_16x16x32_bf16 v[112:115], v[144:147], v[200:203], v[112:115]
	s_waitcnt lgkmcnt(0)
	s_mul_i32 s69, s58, 0x9800
	v_add3_u32 v239, s69, v165, v167
	ds_read_b128 v[228:231], v239
	ds_read_b128 v[232:235], v239 offset:4608
	ds_read_b128 v[240:243], v239 offset:64
	ds_read_b128 v[244:247], v239 offset:4672
	ds_read_b128 v[248:251], v239 offset:128
	v_mfma_f32_16x16x32_bf16 v[108:111], v[172:175], v[200:203], v[108:111]
	v_mfma_f32_16x16x32_bf16 v[72:75], v[192:195], v[200:203], v[72:75]
	v_mfma_f32_16x16x32_bf16 v[68:71], v[196:199], v[200:203], v[68:71]
	v_mfma_f32_16x16x32_bf16 v[64:67], v[128:131], v[200:203], v[64:67]
	v_mfma_f32_16x16x32_bf16 v[28:31], v[132:135], v[204:207], v[28:31]
	v_mfma_f32_16x16x32_bf16 v[24:27], v[136:139], v[204:207], v[24:27]
	v_mfma_f32_16x16x32_bf16 v[20:23], v[140:143], v[204:207], v[20:23]
	v_mfma_f32_16x16x32_bf16 v[16:19], v[144:147], v[204:207], v[16:19]
	v_mfma_f32_16x16x32_bf16 v[12:15], v[172:175], v[204:207], v[12:15]
	v_mfma_f32_16x16x32_bf16 v[8:11], v[192:195], v[204:207], v[8:11]
	v_mfma_f32_16x16x32_bf16 v[4:7], v[196:199], v[204:207], v[4:7]
	v_mfma_f32_16x16x32_bf16 v[0:3], v[128:131], v[204:207], v[0:3]
	s_mov_b64 s[68:69], 0x100
	v_lshl_add_u64 v[158:159], v[158:159], 0, s[68:69]
	s_mov_b64 s[68:69], 0x180000
	s_add_i32 s41, s41, 2
	v_lshl_add_u64 v[160:161], v[160:161], 0, s[68:69]
	v_add_u32_e32 v170, 0x200, v170
	s_cmp_ge_u32 s59, s40
	s_mov_b32 s63, s58
	s_barrier
	s_cbranch_scc1 .LBB0_128
